# scan: section D and Amat@v fragment reads issued up front (MFMAs back to back); attention first PV tr_reads hoisted above the prefetch address math
# speedup vs baseline: 1.0065x; 1.0017x over previous
; __device__ __forceinline__ unsigned pk2(float lo, float hi) { f32x2_t v = {lo, hi}; bf16x2_t b = __builtin_convertvector(v, bf16x2_t); return __builtin_bit_cast(unsigned, b); }
; #define OPAQUE_TID(name) int name = MK_TID; asm volatile("" : "+v"(name))
; __device__ __forceinline__ void scan_unit(const int unit, const Args& a, unsigned char* lds, const int mk_wid) {
;     ...
;             if (wid < 4) { OPAQUE_TID(t_); const int r32 = t_ & 31, hi = (t_ >> 5) & 1;
;                 const int jt = wid >> 1, it = wid & 1; f32x16 ct = f32x16{};
;                 const u16* kp = ke + (jt * 32 + r32) * QP + hi * 8; const u16* qp = qe + (it * 32 + r32) * QP + hi * 8;
; #pragma unroll
;                 for (int kb = 0; kb < 8; ++kb) ct = __builtin_amdgcn_mfma_f32_32x32x16_bf16(*(const bf16x8*)(kp + kb * 16), *(const bf16x8*)(qp + kb * 16), ct, 0, 0, 0);
;                 const int i = it * 32 + r32;
; #pragma unroll
;                 for (int rg = 0; rg < 4; ++rg) { const int j0 = jt * 32 + 8 * rg + 4 * hi;
;                     const float x0 = (j0 + 0 <= i) ? ct[4 * rg + 0] : 0.f, x1 = (j0 + 1 <= i) ? ct[4 * rg + 1] : 0.f, x2 = (j0 + 2 <= i) ? ct[4 * rg + 2] : 0.f, x3 = (j0 + 3 <= i) ? ct[4 * rg + 3] : 0.f;
;                     v2u w; w.x = pk2(x0, x1); w.y = pk2(x2, x3); *(v2u*)(am + i * AP + j0) = w; } }
.Lscan_pf_nolr:
.LBB0_435:
	s_cmp_gt_u32 s5, 3
	s_cselect_b32 s4, 39, 3
	s_add_i32 s4, s4, s50
	s_sub_i32 s4, s4, 38
	s_and_b64 s[26:27], s[2:3], exec
	s_cselect_b32 s42, s5, s4
	s_cmp_gt_i32 s42, 3
	s_cselect_b64 s[26:27], -1, 0
	s_cmp_lt_i32 s42, 4
	s_cselect_b64 s[34:35], -1, 0
	s_and_b64 vcc, exec, s[34:35]
	s_waitcnt lgkmcnt(0)
	s_barrier
	s_cbranch_vccnz .LBB0_439
	s_andn2_b64 vcc, exec, s[24:25]
	s_cbranch_vccnz .LBB0_438
	v_mbcnt_lo_u32_b32 v64, -1, 0
	v_mbcnt_hi_u32_b32 v64, -1, v64
	s_nop 0
	v_add_u32_e32 v64, s72, v64
	s_nop 0
	v_and_b32_e32 v68, 31, v64
	v_bfe_u32 v154, v64, 5, 1
	v_or_b32_e32 v64, s46, v68
	v_mul_lo_u32 v64, v64, s51
	v_lshlrev_b32_e32 v69, 4, v154
	v_add3_u32 v157, 0, v64, v69
	v_or_b32_e32 v158, s47, v68
	v_mul_u32_u24_e32 v68, 0x110, v158
	v_add3_u32 v159, 0, v68, v69
	ds_read_b128 v[170:173], v157 offset:17408
	ds_read_b128 v[174:177], v159
	ds_read_b128 v[178:181], v157 offset:17440
	ds_read_b128 v[182:185], v159 offset:32
	ds_read_b128 v[186:189], v157 offset:17472
	ds_read_b128 v[190:193], v159 offset:64
	ds_read_b128 v[194:197], v157 offset:17504
	ds_read_b128 v[198:201], v159 offset:96
	ds_read_b128 v[202:205], v157 offset:17536
	ds_read_b128 v[206:209], v159 offset:128
	ds_read_b128 v[210:213], v157 offset:17568
	ds_read_b128 v[214:217], v159 offset:160
	ds_read_b128 v[218:221], v157 offset:17600
	ds_read_b128 v[222:225], v159 offset:192
	ds_read_b128 v[226:229], v157 offset:17632
	v_lshl_or_b32 v154, v154, 2, s46
	v_cmp_le_u32_e32 vcc, v154, v158
	v_or_b32_e32 v161, 2, v154
	v_or_b32_e32 v162, 3, v154
	v_or_b32_e32 v164, 8, v154
	v_mul_u32_u24_e32 v160, 0x90, v158
	v_lshlrev_b32_e32 v163, 1, v154
	s_waitcnt lgkmcnt(13)
	v_mfma_f32_32x32x16_bf16 v[64:79], v[170:173], v[174:177], 0
	ds_read_b128 v[230:233], v159 offset:224
	v_or_b32_e32 v80, 10, v154
	v_or_b32_e32 v81, 11, v154
	v_or_b32_e32 v82, 16, v154
	v_or_b32_e32 v83, 18, v154
	v_or_b32_e32 v84, 19, v154
	v_or_b32_e32 v85, 24, v154
	v_add3_u32 v86, s57, v160, v163
	s_waitcnt lgkmcnt(12)
	v_mfma_f32_32x32x16_bf16 v[64:79], v[178:181], v[182:185], v[64:79]
	s_waitcnt lgkmcnt(10)
	v_mfma_f32_32x32x16_bf16 v[64:79], v[186:189], v[190:193], v[64:79]
	s_waitcnt lgkmcnt(8)
	v_mfma_f32_32x32x16_bf16 v[64:79], v[194:197], v[198:201], v[64:79]
	s_waitcnt lgkmcnt(6)
	v_mfma_f32_32x32x16_bf16 v[64:79], v[202:205], v[206:209], v[64:79]
	s_waitcnt lgkmcnt(4)
	v_mfma_f32_32x32x16_bf16 v[64:79], v[210:213], v[214:217], v[64:79]
	s_waitcnt lgkmcnt(2)
	v_mfma_f32_32x32x16_bf16 v[64:79], v[218:221], v[222:225], v[64:79]
	s_waitcnt lgkmcnt(0)
	v_mfma_f32_32x32x16_bf16 v[64:79], v[226:229], v[230:233], v[64:79]
	s_nop 11
	v_cndmask_b32_e32 v64, 0, v64, vcc
	v_cmp_lt_u32_e32 vcc, v154, v158
	s_nop 1
	v_cndmask_b32_e32 v65, 0, v65, vcc
	v_cmp_le_u32_e32 vcc, v161, v158
	v_cvt_pk_bf16_f32 v64, v64, v65
	s_nop 0
	v_cndmask_b32_e32 v66, 0, v66, vcc
	v_cmp_le_u32_e32 vcc, v162, v158
	s_nop 1
	v_cndmask_b32_e32 v67, 0, v67, vcc
	v_cmp_le_u32_e32 vcc, v164, v158
	v_cvt_pk_bf16_f32 v65, v66, v67
	s_nop 0
	v_cndmask_b32_e32 v68, 0, v68, vcc
	v_cmp_lt_u32_e32 vcc, v164, v158
	s_nop 1
	v_cndmask_b32_e32 v69, 0, v69, vcc
	v_cmp_le_u32_e32 vcc, v80, v158
	v_cvt_pk_bf16_f32 v66, v68, v69
	s_nop 0
	v_cndmask_b32_e32 v70, 0, v70, vcc
	v_cmp_le_u32_e32 vcc, v81, v158
	s_nop 1
	v_cndmask_b32_e32 v71, 0, v71, vcc
	v_cmp_le_u32_e32 vcc, v82, v158
	v_cvt_pk_bf16_f32 v67, v70, v71
	ds_write2_b64 v86, v[64:65], v[66:67] offset1:2
	v_cndmask_b32_e32 v72, 0, v72, vcc
	v_cmp_lt_u32_e32 vcc, v82, v158
	v_or_b32_e32 v65, 26, v154
	v_or_b32_e32 v66, 27, v154
	v_cndmask_b32_e32 v73, 0, v73, vcc
	v_cmp_le_u32_e32 vcc, v83, v158
	v_cvt_pk_bf16_f32 v68, v72, v73
	s_nop 0
	v_cndmask_b32_e32 v74, 0, v74, vcc
	v_cmp_le_u32_e32 vcc, v84, v158
	s_nop 1
	v_cndmask_b32_e32 v75, 0, v75, vcc
	v_cmp_le_u32_e32 vcc, v85, v158
	v_cvt_pk_bf16_f32 v69, v74, v75
	s_nop 0
	v_cndmask_b32_e32 v76, 0, v76, vcc
	v_cmp_lt_u32_e32 vcc, v85, v158
	s_nop 1
	v_cndmask_b32_e32 v64, 0, v77, vcc
	v_cmp_le_u32_e32 vcc, v65, v158
	v_cvt_pk_bf16_f32 v64, v76, v64
	s_nop 0
	v_cndmask_b32_e32 v65, 0, v78, vcc
	v_cmp_le_u32_e32 vcc, v66, v158
	s_nop 1
	v_cndmask_b32_e32 v66, 0, v79, vcc
	v_cvt_pk_bf16_f32 v65, v65, v66
	ds_write2_b64 v86, v[68:69], v[64:65] offset0:4 offset1:6

; #define GLA_SBAR() __builtin_amdgcn_sched_barrier(0)
; #define GLA_LOADV() do { vl0 = tr_read<v_rd_off(0, 0, 0)>(vb); vh0 = tr_read<v_rd_off(0, 0, 1)>(vb); vl1 = tr_read<v_rd_off(0, 1, 0)>(vb); vh1 = tr_read<v_rd_off(0, 1, 1)>(vb); \
;               vl2 = tr_read<v_rd_off(0, 2, 0)>(vb); vh2 = tr_read<v_rd_off(0, 2, 1)>(vb); vl3 = tr_read<v_rd_off(0, 3, 0)>(vb); vh3 = tr_read<v_rd_off(0, 3, 1)>(vb); } while (0)
; __device__ __forceinline__ void scan_unit(const int unit, const Args& a, unsigned char* lds, const int mk_wid) {
;     ...
;                     { const u16* p0 = qe + r32 * QP + cb + 4 * hi; const v2u lo = *(const v2u*)p0, hh = *(const v2u*)(p0 + 8); v4u aw = {lo.x, lo.y, hh.x, hh.y};
;                       o0 = __builtin_amdgcn_mfma_f32_32x32x16_bf16(__builtin_bit_cast(bf16x8, aw), sb, o0, 0, 0, 0); }
;                     { const u16* p1 = qe + (32 + r32) * QP + cb + 4 * hi; const v2u lo = *(const v2u*)p1, hh = *(const v2u*)(p1 + 8); v4u aw = {lo.x, lo.y, hh.x, hh.y};
;                       o1 = __builtin_amdgcn_mfma_f32_32x32x16_bf16(__builtin_bit_cast(bf16x8, aw), sb, o1, 0, 0, 0); } }
;               GLA_LOADV();
;               asm volatile("s_waitcnt lgkmcnt(0)" ::: "memory"); GLA_SBAR();
;               { const u16* a0 = am + r32 * AP + hi * 8; const u16* a1 = am + (32 + r32) * AP + hi * 8;
;                 o0 = __builtin_amdgcn_mfma_f32_32x32x16_bf16(*(const bf16x8*)(a0), GLA_PK(vl0, vh0), o0, 0, 0, 0);
;                 o0 = __builtin_amdgcn_mfma_f32_32x32x16_bf16(*(const bf16x8*)(a0 + 16), GLA_PK(vl1, vh1), o0, 0, 0, 0);
;                 o1 = __builtin_amdgcn_mfma_f32_32x32x16_bf16(*(const bf16x8*)(a1), GLA_PK(vl0, vh0), o1, 0, 0, 0);
;                 o1 = __builtin_amdgcn_mfma_f32_32x32x16_bf16(*(const bf16x8*)(a1 + 16), GLA_PK(vl1, vh1), o1, 0, 0, 0);
;                 o1 = __builtin_amdgcn_mfma_f32_32x32x16_bf16(*(const bf16x8*)(a1 + 32), GLA_PK(vl2, vh2), o1, 0, 0, 0);
;                 o1 = __builtin_amdgcn_mfma_f32_32x32x16_bf16(*(const bf16x8*)(a1 + 48), GLA_PK(vl3, vh3), o1, 0, 0, 0); }
.LBB0_442:
	v_and_b32_e32 v168, 31, v64
	v_mul_u32_u24_e32 v64, 0x110, v168
	v_lshlrev_b32_e32 v65, 4, v157
	v_add3_u32 v144, 0, v64, v65
	ds_read_b128 v[170:173], v144
	ds_read_b128 v[174:177], v144 offset:32
	ds_read_b128 v[178:181], v144 offset:8704
	ds_read_b128 v[182:185], v144 offset:8736
	ds_read_b128 v[186:189], v144 offset:64
	ds_read_b128 v[190:193], v144 offset:8768
	ds_read_b128 v[194:197], v144 offset:96
	ds_read_b128 v[198:201], v144 offset:8800
	ds_read_b128 v[202:205], v144 offset:128
	ds_read_b128 v[206:209], v144 offset:8832
	ds_read_b128 v[210:213], v144 offset:160
	ds_read_b128 v[214:217], v144 offset:8864
	ds_read_b128 v[218:221], v144 offset:192
	ds_read_b128 v[222:225], v144 offset:8896
	ds_read_b128 v[226:229], v144 offset:224
	v_cvt_pk_bf16_f32 v80, v0, v1
	v_cvt_pk_bf16_f32 v81, v2, v3
	v_cvt_pk_bf16_f32 v82, v4, v5
	v_cvt_pk_bf16_f32 v83, v6, v7
	s_waitcnt lgkmcnt(14)
	s_nop 0
	v_mfma_f32_32x32x16_bf16 v[64:79], v[170:173], v[80:83], 0
	ds_read_b128 v[230:233], v144 offset:8928
	v_cvt_pk_bf16_f32 v140, v8, v9
	v_cvt_pk_bf16_f32 v141, v10, v11
	v_cvt_pk_bf16_f32 v142, v12, v13
	v_cvt_pk_bf16_f32 v143, v14, v15
	v_cvt_pk_bf16_f32 v160, v56, v57
	v_cvt_pk_bf16_f32 v161, v58, v59
	v_cvt_pk_bf16_f32 v162, v60, v61
	v_cvt_pk_bf16_f32 v163, v62, v63
	s_waitcnt lgkmcnt(14)
	s_nop 0
	v_mfma_f32_32x32x16_bf16 v[64:79], v[174:177], v[140:143], v[64:79]
	s_waitcnt lgkmcnt(13)
	v_mfma_f32_32x32x16_bf16 v[80:95], v[178:181], v[80:83], 0
	s_waitcnt lgkmcnt(12)
	v_mfma_f32_32x32x16_bf16 v[80:95], v[182:185], v[140:143], v[80:95]
	v_cvt_pk_bf16_f32 v140, v16, v17
	v_cvt_pk_bf16_f32 v141, v18, v19
	v_cvt_pk_bf16_f32 v142, v20, v21
	v_cvt_pk_bf16_f32 v143, v22, v23
	s_waitcnt lgkmcnt(11)
	s_nop 0
	v_mfma_f32_32x32x16_bf16 v[64:79], v[186:189], v[140:143], v[64:79]
	s_waitcnt lgkmcnt(10)
	v_mfma_f32_32x32x16_bf16 v[80:95], v[190:193], v[140:143], v[80:95]
	v_cvt_pk_bf16_f32 v140, v24, v25
	v_cvt_pk_bf16_f32 v141, v26, v27
	v_cvt_pk_bf16_f32 v142, v28, v29
	v_cvt_pk_bf16_f32 v143, v30, v31
	s_waitcnt lgkmcnt(9)
	s_nop 0
	v_mfma_f32_32x32x16_bf16 v[64:79], v[194:197], v[140:143], v[64:79]
	s_waitcnt lgkmcnt(8)
	v_mfma_f32_32x32x16_bf16 v[80:95], v[198:201], v[140:143], v[80:95]
	v_cvt_pk_bf16_f32 v140, v32, v33
	v_cvt_pk_bf16_f32 v141, v34, v35
	v_cvt_pk_bf16_f32 v142, v36, v37
	v_cvt_pk_bf16_f32 v143, v38, v39
	s_waitcnt lgkmcnt(7)
	s_nop 0
	v_mfma_f32_32x32x16_bf16 v[64:79], v[202:205], v[140:143], v[64:79]
	s_waitcnt lgkmcnt(6)
	v_mfma_f32_32x32x16_bf16 v[80:95], v[206:209], v[140:143], v[80:95]
	v_cvt_pk_bf16_f32 v140, v40, v41
	v_cvt_pk_bf16_f32 v141, v42, v43
	v_cvt_pk_bf16_f32 v142, v44, v45
	v_cvt_pk_bf16_f32 v143, v46, v47
	s_waitcnt lgkmcnt(5)
	s_nop 0
	v_mfma_f32_32x32x16_bf16 v[64:79], v[210:213], v[140:143], v[64:79]
	s_waitcnt lgkmcnt(4)
	v_mfma_f32_32x32x16_bf16 v[80:95], v[214:217], v[140:143], v[80:95]
	v_cvt_pk_bf16_f32 v140, v48, v49
	v_cvt_pk_bf16_f32 v141, v50, v51
	v_cvt_pk_bf16_f32 v142, v52, v53
	v_cvt_pk_bf16_f32 v143, v54, v55
	s_waitcnt lgkmcnt(3)
	s_nop 0
	v_mfma_f32_32x32x16_bf16 v[64:79], v[218:221], v[140:143], v[64:79]
	s_waitcnt lgkmcnt(2)
	v_mfma_f32_32x32x16_bf16 v[80:95], v[222:225], v[140:143], v[80:95]
	v_mul_u32_u24_e32 v236, 0x90, v168
	v_lshlrev_b32_e32 v237, 4, v157
	v_add3_u32 v236, s57, v236, v237
	ds_read_b128 v[170:173], v236
	ds_read_b128 v[174:177], v236 offset:32
	ds_read_b128 v[178:181], v236 offset:4608
	ds_read_b128 v[182:185], v236 offset:4640
	ds_read_b128 v[186:189], v236 offset:4672
	ds_read_b128 v[190:193], v236 offset:4704
	ds_read_b64_tr_b16 v[136:137], v158 offset:0
	s_waitcnt lgkmcnt(8)
	v_mfma_f32_32x32x16_bf16 v[64:79], v[226:229], v[160:163], v[64:79]
	ds_read_b64_tr_b16 v[138:139], v158 offset:0x800
	ds_read_b64_tr_b16 v[140:141], v158 offset:0x1000
	ds_read_b64_tr_b16 v[142:143], v158 offset:0x1800
	ds_read_b64_tr_b16 v[144:145], v158 offset:0x2000
	ds_read_b64_tr_b16 v[146:147], v158 offset:0x2800
	ds_read_b64_tr_b16 v[148:149], v158 offset:0x3000
	ds_read_b64_tr_b16 v[150:151], v158 offset:0x3800
	s_waitcnt lgkmcnt(0)
; __device__ __forceinline__ int crow(int r, int hi) { return (r & 3) + 8 * (r >> 2) + 4 * hi; }
; __device__ __forceinline__ u16 f2bf(float f) { return (u16)(pk2(f, 0.f) & 0xffffu); }
; __device__ __forceinline__ void scan_unit(const int unit, const Args& a, unsigned char* lds, const int mk_wid) {
;     ...
;               { const u16* a0 = am + r32 * AP + hi * 8; const u16* a1 = am + (32 + r32) * AP + hi * 8;
;                 o0 = __builtin_amdgcn_mfma_f32_32x32x16_bf16(*(const bf16x8*)(a0), GLA_PK(vl0, vh0), o0, 0, 0, 0);
;                 o0 = __builtin_amdgcn_mfma_f32_32x32x16_bf16(*(const bf16x8*)(a0 + 16), GLA_PK(vl1, vh1), o0, 0, 0, 0);
;                 o1 = __builtin_amdgcn_mfma_f32_32x32x16_bf16(*(const bf16x8*)(a1), GLA_PK(vl0, vh0), o1, 0, 0, 0);
;                 o1 = __builtin_amdgcn_mfma_f32_32x32x16_bf16(*(const bf16x8*)(a1 + 16), GLA_PK(vl1, vh1), o1, 0, 0, 0);
;                 o1 = __builtin_amdgcn_mfma_f32_32x32x16_bf16(*(const bf16x8*)(a1 + 32), GLA_PK(vl2, vh2), o1, 0, 0, 0);
;                 o1 = __builtin_amdgcn_mfma_f32_32x32x16_bf16(*(const bf16x8*)(a1 + 48), GLA_PK(vl3, vh3), o1, 0, 0, 0); }
;               { u16* ow = ot + (4 * hi) * 256 + vt * 32 + r32;
; #pragma unroll
;                 for (int r = 0; r < 16; ++r) { const int i0 = crow(r, 0); ow[i0 * 256] = f2bf(o0[r]); ow[(i0 + 32) * 256] = f2bf(o1[r]); } }
	v_mfma_f32_32x32x16_bf16 v[80:95], v[230:233], v[160:163], v[80:95]
	s_mov_b32 s34, s42
	v_mfma_f32_32x32x16_bf16 v[64:79], v[170:173], v[136:139], v[64:79]
	v_mfma_f32_32x32x16_bf16 v[64:79], v[174:177], v[140:143], v[64:79]
	v_mfma_f32_32x32x16_bf16 v[80:95], v[178:181], v[136:139], v[80:95]
	v_mfma_f32_32x32x16_bf16 v[80:95], v[182:185], v[140:143], v[80:95]
	v_lshlrev_b32_e32 v234, 11, v157
	v_lshlrev_b32_e32 v235, 1, v168
	v_add3_u32 v234, s49, v234, v235
	v_and_b32_e32 v235, 1, v168
	v_mul_u32_u24_e32 v235, 0x1fe, v235
	v_add_u32_e32 v234, v234, v235
	v_mfma_f32_32x32x16_bf16 v[80:95], v[186:189], v[144:147], v[80:95]
	v_mfma_f32_32x32x16_bf16 v[80:95], v[190:193], v[148:151], v[80:95]
	s_mov_b32 vcc_lo, 0x55555555
	s_mov_b32 vcc_hi, 0x55555555
	s_nop 1
	v_cndmask_b32_dpp v170, v65, v64, vcc quad_perm:[1,0,3,2] row_mask:0xf bank_mask:0xf
	v_cndmask_b32_dpp v171, v67, v66, vcc quad_perm:[1,0,3,2] row_mask:0xf bank_mask:0xf
	v_cndmask_b32_dpp v172, v69, v68, vcc quad_perm:[1,0,3,2] row_mask:0xf bank_mask:0xf
	v_cndmask_b32_dpp v173, v71, v70, vcc quad_perm:[1,0,3,2] row_mask:0xf bank_mask:0xf
	v_cndmask_b32_dpp v174, v73, v72, vcc quad_perm:[1,0,3,2] row_mask:0xf bank_mask:0xf
	v_cndmask_b32_dpp v175, v75, v74, vcc quad_perm:[1,0,3,2] row_mask:0xf bank_mask:0xf
	v_cndmask_b32_dpp v176, v77, v76, vcc quad_perm:[1,0,3,2] row_mask:0xf bank_mask:0xf
	v_cndmask_b32_dpp v177, v79, v78, vcc quad_perm:[1,0,3,2] row_mask:0xf bank_mask:0xf
	s_nop 1
	v_cndmask_b32_dpp v178, v81, v80, vcc quad_perm:[1,0,3,2] row_mask:0xf bank_mask:0xf
	v_cndmask_b32_dpp v179, v83, v82, vcc quad_perm:[1,0,3,2] row_mask:0xf bank_mask:0xf
	v_cndmask_b32_dpp v180, v85, v84, vcc quad_perm:[1,0,3,2] row_mask:0xf bank_mask:0xf
	v_cndmask_b32_dpp v181, v87, v86, vcc quad_perm:[1,0,3,2] row_mask:0xf bank_mask:0xf
	v_cndmask_b32_dpp v182, v89, v88, vcc quad_perm:[1,0,3,2] row_mask:0xf bank_mask:0xf
	v_cndmask_b32_dpp v183, v91, v90, vcc quad_perm:[1,0,3,2] row_mask:0xf bank_mask:0xf
	v_cndmask_b32_dpp v184, v93, v92, vcc quad_perm:[1,0,3,2] row_mask:0xf bank_mask:0xf
	v_cndmask_b32_dpp v185, v95, v94, vcc quad_perm:[1,0,3,2] row_mask:0xf bank_mask:0xf
	s_mov_b32 vcc_lo, 0xaaaaaaaa
	s_mov_b32 vcc_hi, 0xaaaaaaaa
	s_nop 1
	v_cndmask_b32_dpp v186, v64, v65, vcc quad_perm:[1,0,3,2] row_mask:0xf bank_mask:0xf
	v_cndmask_b32_dpp v187, v66, v67, vcc quad_perm:[1,0,3,2] row_mask:0xf bank_mask:0xf
	v_cndmask_b32_dpp v188, v68, v69, vcc quad_perm:[1,0,3,2] row_mask:0xf bank_mask:0xf
	v_cndmask_b32_dpp v189, v70, v71, vcc quad_perm:[1,0,3,2] row_mask:0xf bank_mask:0xf
	v_cndmask_b32_dpp v190, v72, v73, vcc quad_perm:[1,0,3,2] row_mask:0xf bank_mask:0xf
	v_cndmask_b32_dpp v191, v74, v75, vcc quad_perm:[1,0,3,2] row_mask:0xf bank_mask:0xf
	v_cndmask_b32_dpp v192, v76, v77, vcc quad_perm:[1,0,3,2] row_mask:0xf bank_mask:0xf
	v_cndmask_b32_dpp v193, v78, v79, vcc quad_perm:[1,0,3,2] row_mask:0xf bank_mask:0xf
	v_cndmask_b32_dpp v194, v80, v81, vcc quad_perm:[1,0,3,2] row_mask:0xf bank_mask:0xf
	v_cndmask_b32_dpp v195, v82, v83, vcc quad_perm:[1,0,3,2] row_mask:0xf bank_mask:0xf
	v_cndmask_b32_dpp v196, v84, v85, vcc quad_perm:[1,0,3,2] row_mask:0xf bank_mask:0xf
	v_cndmask_b32_dpp v197, v86, v87, vcc quad_perm:[1,0,3,2] row_mask:0xf bank_mask:0xf
	v_cndmask_b32_dpp v198, v88, v89, vcc quad_perm:[1,0,3,2] row_mask:0xf bank_mask:0xf
	v_cndmask_b32_dpp v199, v90, v91, vcc quad_perm:[1,0,3,2] row_mask:0xf bank_mask:0xf
	v_cndmask_b32_dpp v200, v92, v93, vcc quad_perm:[1,0,3,2] row_mask:0xf bank_mask:0xf
	v_cndmask_b32_dpp v201, v94, v95, vcc quad_perm:[1,0,3,2] row_mask:0xf bank_mask:0xf
	v_cvt_pk_bf16_f32 v170, v170, v186
	ds_write_b32 v234, v170
	v_cvt_pk_bf16_f32 v171, v171, v187
	ds_write_b32 v234, v171 offset:1024
	v_cvt_pk_bf16_f32 v172, v172, v188
	ds_write_b32 v234, v172 offset:4096
	v_cvt_pk_bf16_f32 v173, v173, v189
	ds_write_b32 v234, v173 offset:5120
	v_cvt_pk_bf16_f32 v174, v174, v190
	ds_write_b32 v234, v174 offset:8192
	v_cvt_pk_bf16_f32 v175, v175, v191
	ds_write_b32 v234, v175 offset:9216
	v_cvt_pk_bf16_f32 v176, v176, v192
	ds_write_b32 v234, v176 offset:12288
	v_cvt_pk_bf16_f32 v177, v177, v193
	ds_write_b32 v234, v177 offset:13312
	v_cvt_pk_bf16_f32 v178, v178, v194
	ds_write_b32 v234, v178 offset:16384
	v_cvt_pk_bf16_f32 v179, v179, v195
	ds_write_b32 v234, v179 offset:17408
	v_cvt_pk_bf16_f32 v180, v180, v196
	ds_write_b32 v234, v180 offset:20480
	v_cvt_pk_bf16_f32 v181, v181, v197
	ds_write_b32 v234, v181 offset:21504
	v_cvt_pk_bf16_f32 v182, v182, v198
	ds_write_b32 v234, v182 offset:24576
	v_cvt_pk_bf16_f32 v183, v183, v199
	ds_write_b32 v234, v183 offset:25600
	v_cvt_pk_bf16_f32 v184, v184, v200
	ds_write_b32 v234, v184 offset:28672
	v_cvt_pk_bf16_f32 v185, v185, v201
	ds_write_b32 v234, v185 offset:29696

; __device__ __forceinline__ void finishSM(f32x16& p0, f32x16& p1, float alpha, float& l_reg, bf16x8& pa0, bf16x8& pa1, bf16x8& pa2, bf16x8& pa3) {
;   for (int r = 0; r < 16; ++r) p1[r] = __builtin_amdgcn_exp2f(p1[r]);
;   float ps = 0; for (int r = 0; r < 16; ++r) ps += p0[r]; for (int r = 0; r < 16; ++r) ps += p1[r];
;   { auto rr = __builtin_amdgcn_permlane32_swap(__float_as_uint(ps), __float_as_uint(ps), false, false);
;     ps = __uint_as_float(rr[0]) + __uint_as_float(rr[1]); }
;   l_reg = l_reg * alpha + ps;
;     ...
;   PK4(p0, 0, pa0); PK4(p0, 8, pa1); PK4(p1, 0, pa2); PK4(p1, 8, pa3);
;     ...
; }
; __device__ __forceinline__ void qkt(f32x16& p0, f32x16& p1, const bf16* Ks, const bf16x8* qr, int r32, int hi) {
;   p0 = f32x16{}; p1 = f32x16{};
;   for (int d0 = 0; d0 < 8; ++d0) { int cb = (d0 * 16 + hi * 8) * 2;
;     bf16x8 b0 = *reinterpret_cast<const bf16x8*>((const char*)Ks + KSWZ(r32, cb));
;     bf16x8 b1 = *reinterpret_cast<const bf16x8*>((const char*)Ks + KSWZ(32 + r32, cb));
;     p0 = __builtin_amdgcn_mfma_f32_32x32x16_bf16(b0, qr[d0], p0, 0, 0, 0);
;     p1 = __builtin_amdgcn_mfma_f32_32x32x16_bf16(b1, qr[d0], p1, 0, 0, 0); }
; }
; __device__ __forceinline__ int v_st(int k, int c) { const int kk = (k & ~0xC) | ((k & 4) << 1) | ((k & 8) >> 1); return ((kk >> 3) * 4 + (c >> 5)) * 512 + ((kk & 7) * 32 + (c & 31)) * 2; }
; __device__ __forceinline__ int v_rd_base(int lane) { return ((lane & 3) << 3) | (((lane >> 2) & 3) << 6) | (((lane >> 4) & 1) << 5) | (((lane >> 5) & 1) << 8); }
; template <int OFF> __device__ __forceinline__ s16x4 tr_read(int vb) {
;   s16x4 r; asm volatile("ds_read_b64_tr_b16 %0, %1 offset:%2" : "=&v"(r) : "v"(vb), "i"(OFF) : "memory"); return r;
; }
; template <int D0> __device__ __forceinline__ void pv_one(f32x16& od, int vb, bf16x8 pa0, bf16x8 pa1, bf16x8 pa2, bf16x8 pa3) {
;   const s16x4 l0 = tr_read<v_rd_off(D0, 0, 0)>(vb), h0 = tr_read<v_rd_off(D0, 0, 1)>(vb), l1 = tr_read<v_rd_off(D0, 1, 0)>(vb), h1 = tr_read<v_rd_off(D0, 1, 1)>(vb);
;   const s16x4 l2 = tr_read<v_rd_off(D0, 2, 0)>(vb), h2 = tr_read<v_rd_off(D0, 2, 1)>(vb), l3 = tr_read<v_rd_off(D0, 3, 0)>(vb), h3 = tr_read<v_rd_off(D0, 3, 1)>(vb);
;   asm volatile("s_waitcnt lgkmcnt(0)" ::: "memory"); SBAR();
;     ...
;   od = __builtin_amdgcn_mfma_f32_32x32x16_bf16(pa0, PK(l0, h0), od, 0, 0, 0);
;   od = __builtin_amdgcn_mfma_f32_32x32x16_bf16(pa1, PK(l1, h1), od, 0, 0, 0);
.LBB0_460:
	ds_read_b128 v[64:67], v191 offset:49152
	ds_read_b128 v[68:71], v191 offset:57344
	ds_read_b128 v[208:211], v192 offset:49152
	ds_read_b128 v[212:215], v192 offset:57344
	ds_read_b128 v[216:219], v193 offset:49152
	ds_read_b128 v[220:223], v193 offset:57344
	v_add_f32_e32 v161, 0, v175
	v_add_f32_e32 v161, v206, v161
	s_waitcnt lgkmcnt(5)
	v_mfma_f32_32x32x16_bf16 v[80:95], v[64:67], v[104:107], 0
	v_add_f32_e32 v161, v173, v161
	v_add_f32_e32 v161, v203, v161
	v_add_f32_e32 v161, v172, v161
	v_add_f32_e32 v161, v174, v161
	v_add_f32_e32 v161, v170, v161
	v_add_f32_e32 v161, v171, v161
	v_add_f32_e32 v161, v167, v161
	s_waitcnt lgkmcnt(4)
	v_mfma_f32_32x32x16_bf16 v[64:79], v[68:71], v[104:107], 0
	v_add_f32_e32 v161, v169, v161
	v_add_f32_e32 v161, v166, v161
	v_add_f32_e32 v161, v168, v161
	v_exp_f32_e32 v152, v152
	v_add_f32_e32 v161, v163, v161
	v_exp_f32_e32 v153, v153
	v_add_f32_e32 v161, v165, v161
	s_waitcnt lgkmcnt(3)
	v_mfma_f32_32x32x16_bf16 v[80:95], v[208:211], v[96:99], v[80:95]
	ds_read_b128 v[208:211], v194 offset:49152
	ds_read_b128 v[224:227], v194 offset:57344
	ds_read_b128 v[228:231], v195 offset:49152
	ds_read_b128 v[232:235], v195 offset:57344
	ds_read_b128 v[236:239], v196 offset:49152
	ds_read_b128 v[240:243], v196 offset:57344
	ds_read_b128 v[244:247], v197 offset:49152
	ds_read_b128 v[248:251], v197 offset:57344
	v_exp_f32_e32 v150, v150
	v_add_f32_e32 v161, v162, v161
	v_exp_f32_e32 v151, v151
	v_add_f32_e32 v161, v164, v161
	v_exp_f32_e32 v148, v148
	v_add_f32_e32 v161, v152, v161
	s_waitcnt lgkmcnt(10)
	v_mfma_f32_32x32x16_bf16 v[64:79], v[212:215], v[96:99], v[64:79]
	v_exp_f32_e32 v149, v149
	v_add_f32_e32 v161, v153, v161
	v_exp_f32_e32 v146, v146
	v_add_f32_e32 v161, v150, v161
	v_exp_f32_e32 v147, v147
	v_add_f32_e32 v161, v151, v161
	v_exp_f32_e32 v144, v144
	s_waitcnt lgkmcnt(9)
	v_mfma_f32_32x32x16_bf16 v[80:95], v[216:219], v[100:103], v[80:95]
	v_add_f32_e32 v161, v148, v161
	ds_read_b128 v[212:215], v198 offset:49152
	ds_read_b128 v[252:255], v198 offset:57344
	v_exp_f32_e32 v145, v145
	v_add_f32_e32 v161, v149, v161
	v_exp_f32_e32 v158, v158
	v_add_f32_e32 v161, v146, v161
	v_exp_f32_e32 v159, v159
	s_waitcnt lgkmcnt(10)
	v_mfma_f32_32x32x16_bf16 v[64:79], v[220:223], v[100:103], v[64:79]
	v_add_f32_e32 v161, v147, v161
	v_exp_f32_e32 v156, v156
	v_add_f32_e32 v161, v144, v161
	v_exp_f32_e32 v157, v157
	v_add_f32_e32 v161, v145, v161
	v_exp_f32_e32 v154, v154
	v_add_f32_e32 v161, v158, v161
	s_waitcnt lgkmcnt(9)
	v_mfma_f32_32x32x16_bf16 v[80:95], v[208:211], v[108:111], v[80:95]
	v_exp_f32_e32 v155, v155
	v_add_f32_e32 v161, v159, v161
	v_add_f32_e32 v161, v156, v161
	v_add_f32_e32 v161, v157, v161
	v_add_f32_e32 v161, v154, v161
	v_add_f32_e32 v200, v155, v161
	v_mov_b32_e32 v201, v200
	s_waitcnt lgkmcnt(8)
	v_mfma_f32_32x32x16_bf16 v[64:79], v[224:227], v[108:111], v[64:79]
	v_cvt_pk_bf16_f32 v202, v175, v206
	v_cvt_pk_bf16_f32 v203, v173, v203
	v_cvt_pk_bf16_f32 v204, v172, v174
	v_permlane32_swap_b32_e32 v200, v201
	v_cvt_pk_bf16_f32 v205, v170, v171
	v_permlane32_swap_b32_e32 v202, v204
	s_waitcnt lgkmcnt(7)
	v_mfma_f32_32x32x16_bf16 v[80:95], v[228:231], v[120:123], v[80:95]
	v_cvt_pk_bf16_f32 v170, v167, v169
	v_cvt_pk_bf16_f32 v171, v166, v168
	v_cvt_pk_bf16_f32 v172, v163, v165
	v_cvt_pk_bf16_f32 v173, v162, v164
	v_cvt_pk_bf16_f32 v162, v152, v153
	v_cvt_pk_bf16_f32 v163, v150, v151
	v_cvt_pk_bf16_f32 v164, v148, v149
	s_waitcnt lgkmcnt(6)
	v_mfma_f32_32x32x16_bf16 v[64:79], v[232:235], v[120:123], v[64:79]
	v_cvt_pk_bf16_f32 v165, v146, v147
	v_cvt_pk_bf16_f32 v166, v144, v145
	v_cvt_pk_bf16_f32 v167, v158, v159
	v_cvt_pk_bf16_f32 v168, v156, v157
	v_cvt_pk_bf16_f32 v169, v154, v155
	v_permlane32_swap_b32_e32 v203, v205
	s_waitcnt lgkmcnt(5)
	v_mfma_f32_32x32x16_bf16 v[80:95], v[236:239], v[124:127], v[80:95]
	v_permlane32_swap_b32_e32 v170, v172
	v_permlane32_swap_b32_e32 v171, v173
	v_permlane32_swap_b32_e32 v162, v164
	v_permlane32_swap_b32_e32 v163, v165
	s_waitcnt lgkmcnt(4)
	v_mfma_f32_32x32x16_bf16 v[64:79], v[240:243], v[124:127], v[64:79]
	v_permlane32_swap_b32_e32 v166, v168
	v_permlane32_swap_b32_e32 v167, v169
	s_waitcnt lgkmcnt(3)
	v_mfma_f32_32x32x16_bf16 v[80:95], v[244:247], v[112:115], v[80:95]
	s_waitcnt lgkmcnt(2)
	v_mfma_f32_32x32x16_bf16 v[64:79], v[248:251], v[112:115], v[64:79]
	s_waitcnt lgkmcnt(1)
	v_mfma_f32_32x32x16_bf16 v[80:95], v[212:215], v[116:119], v[80:95]
	s_waitcnt lgkmcnt(0)
	v_mfma_f32_32x32x16_bf16 v[64:79], v[252:255], v[116:119], v[64:79]
	ds_read_b64_tr_b16 v[206:207], v186 offset:0
	ds_read_b64_tr_b16 v[208:209], v186 offset:0x800
	ds_read_b64_tr_b16 v[210:211], v186 offset:0x1000
	ds_read_b64_tr_b16 v[212:213], v186 offset:0x1800
	ds_read_b64_tr_b16 v[214:215], v186 offset:0x2000
	ds_read_b64_tr_b16 v[216:217], v186 offset:0x2800
	ds_read_b64_tr_b16 v[218:219], v186 offset:0x3000
	ds_read_b64_tr_b16 v[220:221], v186 offset:0x3800
	v_add_co_u32_e32 v144, vcc, s75, v178
	s_nop 1
	v_addc_co_u32_e32 v145, vcc, -1, v179, vcc
	v_add_co_u32_e32 v148, vcc, s76, v178
	s_nop 1
	v_addc_co_u32_e32 v149, vcc, -1, v179, vcc
	v_add_co_u32_e32 v152, vcc, s77, v178
	global_load_dwordx4 v[144:147], v[144:145], off
	s_nop 0
	global_load_dwordx4 v[148:151], v[148:149], off
	v_addc_co_u32_e32 v153, vcc, -1, v179, vcc
	v_add_co_u32_e32 v156, vcc, s78, v178
	s_nop 1
	v_addc_co_u32_e32 v157, vcc, -1, v179, vcc
	global_load_dwordx4 v[152:155], v[152:153], off
	s_nop 0
	global_load_dwordx4 v[156:159], v[156:157], off
	s_waitcnt lgkmcnt(0)
; __device__ __forceinline__ void partialSM(f32x16& p0, f32x16& p1, float& m_reg, float& mn, float& alpha) {
;   constexpr float C = SCALE * 1.4426950408889634f;
;   float pmax = p0[0]; for (int r = 1; r < 16; ++r) pmax = fmaxf(pmax, p0[r]); for (int r = 0; r < 16; ++r) pmax = fmaxf(pmax, p1[r]);
;   { auto rr = __builtin_amdgcn_permlane32_swap(__float_as_uint(pmax), __float_as_uint(pmax), false, false);
;     pmax = fmaxf(__uint_as_float(rr[0]), __uint_as_float(rr[1])); }
;   if (__builtin_expect(__all(pmax - m_reg <= THR / SCALE), 1)) { mn = m_reg; alpha = 1.f; }
;   else { mn = fmaxf(m_reg, pmax); alpha = __builtin_amdgcn_exp2f((m_reg - mn) * C); m_reg = mn; }
;   float mnC = -mn * C;
;   for (int r = 0; r < 16; ++r) p0[r] = fmaf(p0[r], C, mnC); for (int r = 0; r < 16; ++r) p1[r] = fmaf(p1[r], C, mnC);
;   for (int r = 0; r < 16; ++r) p0[r] = __builtin_amdgcn_exp2f(p0[r]);
; }
; __device__ __forceinline__ void finishSM(f32x16& p0, f32x16& p1, float alpha, float& l_reg, bf16x8& pa0, bf16x8& pa1, bf16x8& pa2, bf16x8& pa3) {
;   for (int r = 0; r < 16; ++r) p1[r] = __builtin_amdgcn_exp2f(p1[r]);
;   float ps = 0; for (int r = 0; r < 16; ++r) ps += p0[r]; for (int r = 0; r < 16; ++r) ps += p1[r];
;   { auto rr = __builtin_amdgcn_permlane32_swap(__float_as_uint(ps), __float_as_uint(ps), false, false);
;     ps = __uint_as_float(rr[0]) + __uint_as_float(rr[1]); }
;   l_reg = l_reg * alpha + ps;
;     ...
;   PK4(p0, 0, pa0); PK4(p0, 8, pa1); PK4(p1, 0, pa2); PK4(p1, 8, pa3);
;     ...
; }
; __device__ __forceinline__ void qkt(f32x16& p0, f32x16& p1, const bf16* Ks, const bf16x8* qr, int r32, int hi) {
;   p0 = f32x16{}; p1 = f32x16{};
;   for (int d0 = 0; d0 < 8; ++d0) { int cb = (d0 * 16 + hi * 8) * 2;
;     bf16x8 b0 = *reinterpret_cast<const bf16x8*>((const char*)Ks + KSWZ(r32, cb));
;     bf16x8 b1 = *reinterpret_cast<const bf16x8*>((const char*)Ks + KSWZ(32 + r32, cb));
;     p0 = __builtin_amdgcn_mfma_f32_32x32x16_bf16(b0, qr[d0], p0, 0, 0, 0);
;     p1 = __builtin_amdgcn_mfma_f32_32x32x16_bf16(b1, qr[d0], p1, 0, 0, 0); }
; }
; __device__ __forceinline__ int v_st(int k, int c) { const int kk = (k & ~0xC) | ((k & 4) << 1) | ((k & 8) >> 1); return ((kk >> 3) * 4 + (c >> 5)) * 512 + ((kk & 7) * 32 + (c & 31)) * 2; }
; __device__ __forceinline__ int v_rd_base(int lane) { return ((lane & 3) << 3) | (((lane >> 2) & 3) << 6) | (((lane >> 4) & 1) << 5) | (((lane >> 5) & 1) << 8); }
	s_nop 0
	v_mfma_f32_32x32x16_bf16 v[0:15], v[202:205], v[206:209], v[0:15]
	ds_read_b64_tr_b16 v[206:207], v186 offset:0x200
	ds_read_b64_tr_b16 v[208:209], v186 offset:0xa00
	v_mfma_f32_32x32x16_bf16 v[0:15], v[170:173], v[210:213], v[0:15]
	ds_read_b64_tr_b16 v[210:211], v186 offset:0x1200
	ds_read_b64_tr_b16 v[212:213], v186 offset:0x1a00
	v_mfma_f32_32x32x16_bf16 v[0:15], v[162:165], v[214:217], v[0:15]
	ds_read_b64_tr_b16 v[214:215], v186 offset:0x2200
	ds_read_b64_tr_b16 v[216:217], v186 offset:0x2a00
	ds_read_b64_tr_b16 v[222:223], v186 offset:0x3200
	ds_read_b64_tr_b16 v[224:225], v186 offset:0x3a00
	s_waitcnt lgkmcnt(0)
	v_mfma_f32_32x32x16_bf16 v[0:15], v[166:169], v[218:221], v[0:15]
	v_mfma_f32_32x32x16_bf16 v[48:63], v[202:205], v[206:209], v[48:63]
	ds_read_b64_tr_b16 v[206:207], v186 offset:0x400
	ds_read_b64_tr_b16 v[208:209], v186 offset:0xc00
	v_mfma_f32_32x32x16_bf16 v[48:63], v[170:173], v[210:213], v[48:63]
	ds_read_b64_tr_b16 v[210:211], v186 offset:0x1400
	ds_read_b64_tr_b16 v[212:213], v186 offset:0x1c00
	v_mfma_f32_32x32x16_bf16 v[48:63], v[162:165], v[214:217], v[48:63]
	ds_read_b64_tr_b16 v[214:215], v186 offset:0x2400
	ds_read_b64_tr_b16 v[216:217], v186 offset:0x2c00
	ds_read_b64_tr_b16 v[218:219], v186 offset:0x3400
	ds_read_b64_tr_b16 v[220:221], v186 offset:0x3c00
	s_waitcnt lgkmcnt(0)
	v_mfma_f32_32x32x16_bf16 v[48:63], v[166:169], v[222:225], v[48:63]
	v_mfma_f32_32x32x16_bf16 v[32:47], v[202:205], v[206:209], v[32:47]
	ds_read_b64_tr_b16 v[206:207], v186 offset:0x600
	ds_read_b64_tr_b16 v[208:209], v186 offset:0xe00
	v_mfma_f32_32x32x16_bf16 v[32:47], v[170:173], v[210:213], v[32:47]
	ds_read_b64_tr_b16 v[210:211], v186 offset:0x1600
	ds_read_b64_tr_b16 v[212:213], v186 offset:0x1e00
	v_mfma_f32_32x32x16_bf16 v[32:47], v[162:165], v[214:217], v[32:47]
	ds_read_b64_tr_b16 v[214:215], v186 offset:0x2600
	ds_read_b64_tr_b16 v[216:217], v186 offset:0x2e00
	ds_read_b64_tr_b16 v[222:223], v186 offset:0x3600
	ds_read_b64_tr_b16 v[224:225], v186 offset:0x3e00
	s_waitcnt lgkmcnt(0)
	v_mfma_f32_32x32x16_bf16 v[32:47], v[166:169], v[218:221], v[32:47]
	v_mfma_f32_32x32x16_bf16 v[16:31], v[202:205], v[206:209], v[16:31]
	v_max_f32_e32 v161, v81, v81
	v_max_f32_e32 v174, v80, v80
	v_max_f32_e32 v161, v174, v161
	v_max3_f32 v161, v161, v82, v83
	v_max3_f32 v161, v161, v84, v85
	v_max3_f32 v161, v161, v86, v87
	v_max3_f32 v161, v161, v88, v89
	v_max3_f32 v161, v161, v90, v91
	v_mfma_f32_32x32x16_bf16 v[16:31], v[170:173], v[210:213], v[16:31]
	v_max3_f32 v161, v161, v92, v93
	v_max3_f32 v161, v161, v94, v95
	v_max3_f32 v161, v161, v64, v65
	v_max3_f32 v161, v161, v66, v67
	v_max3_f32 v161, v161, v68, v69
	v_max3_f32 v161, v161, v70, v71
	v_max3_f32 v161, v161, v72, v73
	v_max3_f32 v161, v161, v74, v75
	v_mfma_f32_32x32x16_bf16 v[16:31], v[162:165], v[214:217], v[16:31]
	v_max3_f32 v161, v161, v76, v77
	v_max3_f32 v161, v161, v78, v79
	v_mov_b32_e32 v170, v161
	s_nop 1
	v_permlane32_swap_b32_e32 v161, v170
	v_max_f32_e32 v162, v170, v170
	v_max_f32_e32 v161, v161, v161
	v_max_f32_e32 v161, v161, v162
	v_max_f32_e32 v163, v160, v160
	v_sub_f32_e32 v162, v161, v160
	v_max_f32_e32 v161, v163, v161
	v_mfma_f32_32x32x16_bf16 v[16:31], v[166:169], v[222:225], v[16:31]
	v_sub_f32_e32 v163, v160, v161
	v_mul_f32_e32 v163, 0x3e0293ee, v163
	v_exp_f32_e32 v163, v163
	v_cmp_ge_f32_e32 vcc, s74, v162
	s_cmp_eq_u64 vcc, exec
	s_cselect_b64 s[4:5], -1, 0
	s_barrier
	s_waitcnt vmcnt(4)
	v_cndmask_b32_e64 v202, v163, 1.0, s[4:5]
	v_cmp_gt_f32_e32 vcc, 1.0, v202
	s_waitcnt vmcnt(7)
	ds_write_b128 v187, v[128:131]
	s_waitcnt vmcnt(6)
	ds_write_b128 v188, v[136:139]
	s_waitcnt vmcnt(5)
	ds_write_b128 v189, v[132:135] offset:32768
	s_waitcnt vmcnt(4)
	ds_write_b128 v190, v[140:143] offset:32768
	s_cbranch_vccz .LBB0_464
	s_and_saveexec_b64 s[14:15], s[2:3]
	ds_write_b32 v183, v202 offset:128
	s_or_b64 exec, exec, s[14:15]
	s_waitcnt lgkmcnt(0)
	v_add_u32_e32 v174, s67, v176
	ds_read_b128 v[162:165], v174 offset:224
	ds_read_b128 v[166:169], v174 offset:192
	ds_read_b128 v[170:173], v174 offset:160
	ds_read_b128 v[204:207], v174 offset:128
	s_waitcnt lgkmcnt(3)
	v_pk_mul_f32 v[12:13], v[12:13], v[162:163]
	s_waitcnt lgkmcnt(2)
	v_pk_mul_f32 v[8:9], v[8:9], v[166:167]
	s_waitcnt lgkmcnt(1)
	v_pk_mul_f32 v[4:5], v[4:5], v[170:171]
	v_pk_mul_f32 v[14:15], v[14:15], v[164:165]
	v_pk_mul_f32 v[10:11], v[10:11], v[168:169]
	v_pk_mul_f32 v[6:7], v[6:7], v[172:173]
	s_waitcnt lgkmcnt(0)
	v_pk_mul_f32 v[2:3], v[2:3], v[206:207]
	v_pk_mul_f32 v[0:1], v[0:1], v[204:205]
	v_pk_mul_f32 v[60:61], v[60:61], v[162:163]
	v_pk_mul_f32 v[56:57], v[56:57], v[166:167]
	v_pk_mul_f32 v[52:53], v[52:53], v[170:171]
	v_pk_mul_f32 v[62:63], v[62:63], v[164:165]
	v_pk_mul_f32 v[58:59], v[58:59], v[168:169]
	v_pk_mul_f32 v[54:55], v[54:55], v[172:173]
	v_pk_mul_f32 v[50:51], v[50:51], v[206:207]
	v_pk_mul_f32 v[48:49], v[48:49], v[204:205]
	v_pk_mul_f32 v[44:45], v[44:45], v[162:163]
	v_pk_mul_f32 v[40:41], v[40:41], v[166:167]
	v_pk_mul_f32 v[36:37], v[36:37], v[170:171]
	v_pk_mul_f32 v[46:47], v[46:47], v[164:165]
	v_pk_mul_f32 v[42:43], v[42:43], v[168:169]
	v_pk_mul_f32 v[38:39], v[38:39], v[172:173]
	v_pk_mul_f32 v[34:35], v[34:35], v[206:207]
	v_pk_mul_f32 v[32:33], v[32:33], v[204:205]
	v_pk_mul_f32 v[28:29], v[28:29], v[162:163]
	v_pk_mul_f32 v[24:25], v[24:25], v[166:167]
	v_pk_mul_f32 v[20:21], v[20:21], v[170:171]
	v_pk_mul_f32 v[30:31], v[30:31], v[164:165]
	v_pk_mul_f32 v[26:27], v[26:27], v[168:169]
	v_pk_mul_f32 v[22:23], v[22:23], v[172:173]
	v_pk_mul_f32 v[18:19], v[18:19], v[206:207]
	v_pk_mul_f32 v[16:17], v[16:17], v[204:205]
; #define SBAR() __builtin_amdgcn_sched_barrier(0)
; #define SLOAD(i, k0) do { sr_[i].vs0 = St::ld8(&Vh[(long)((k0) + sr) * LDK + sc]); sr_[i].vs1 = St::ld8(&Vh[(long)((k0) + 32 + sr) * LDK + sc]); \
;     sr_[i].ks0 = St::ld8(&Kh[(long)((k0) + sr) * LDK + sc]); sr_[i].ks1 = St::ld8(&Kh[(long)((k0) + 32 + sr) * LDK + sc]); } while (0)
; __device__ __forceinline__ void partialSM(f32x16& p0, f32x16& p1, float& m_reg, float& mn, float& alpha) {
;     ...
;   float mnC = -mn * C;
;   for (int r = 0; r < 16; ++r) p0[r] = fmaf(p0[r], C, mnC); for (int r = 0; r < 16; ++r) p1[r] = fmaf(p1[r], C, mnC);
;   for (int r = 0; r < 16; ++r) p0[r] = __builtin_amdgcn_exp2f(p0[r]);
; }
; __device__ __forceinline__ void finishSM(f32x16& p0, f32x16& p1, float alpha, float& l_reg, bf16x8& pa0, bf16x8& pa1, bf16x8& pa2, bf16x8& pa3) {
;   for (int r = 0; r < 16; ++r) p1[r] = __builtin_amdgcn_exp2f(p1[r]);
;   float ps = 0; for (int r = 0; r < 16; ++r) ps += p0[r]; for (int r = 0; r < 16; ++r) ps += p1[r];
;   { auto rr = __builtin_amdgcn_permlane32_swap(__float_as_uint(ps), __float_as_uint(ps), false, false);
;     ps = __uint_as_float(rr[0]) + __uint_as_float(rr[1]); }
;   l_reg = l_reg * alpha + ps;
;     ...
;   PK4(p0, 0, pa0); PK4(p0, 8, pa1); PK4(p1, 0, pa2); PK4(p1, 8, pa3);
;     ...
; }
; __device__ __forceinline__ void qkt(f32x16& p0, f32x16& p1, const bf16* Ks, const bf16x8* qr, int r32, int hi) {
;   p0 = f32x16{}; p1 = f32x16{};
;   for (int d0 = 0; d0 < 8; ++d0) { int cb = (d0 * 16 + hi * 8) * 2;
;     bf16x8 b0 = *reinterpret_cast<const bf16x8*>((const char*)Ks + KSWZ(r32, cb));
;     bf16x8 b1 = *reinterpret_cast<const bf16x8*>((const char*)Ks + KSWZ(32 + r32, cb));
;     p0 = __builtin_amdgcn_mfma_f32_32x32x16_bf16(b0, qr[d0], p0, 0, 0, 0);
;     p1 = __builtin_amdgcn_mfma_f32_32x32x16_bf16(b1, qr[d0], p1, 0, 0, 0); }
; __device__ __forceinline__ void attn_unit(const bf16* Qb, const bf16* __restrict__ Kh, const bf16* __restrict__ Vh, bf16* Ob, int seq, char* lds,
;                                           const float* __restrict__ rope, const float* __restrict__ qg, const int mk_wid) {
;     ...
;     SBAR(); qkt(pA0, pA1, K_lds, qr, r32, hi);
;     finishSM(pB0, pB1, alB, l_reg, pa0, pa1, pa2, pa3); SBAR();
;     if (j + 3 < NT) SLOAD(SE, (j + 3) * KVBLK); SBAR();
;     pv_d0(o, vb0 + (int)SHM_V, pa0, pa1, pa2, pa3); partialSM(pA0, pA1, m_reg, mnA, alA);
.LBB0_464:
	v_cndmask_b32_e64 v203, v161, v160, s[4:5]
	v_mul_f32_e32 v204, 0xbe0293ee, v203
	v_fmamk_f32 v80, v80, 0x3e0293ee, v204
	v_fmamk_f32 v81, v81, 0x3e0293ee, v204
	v_fmamk_f32 v82, v82, 0x3e0293ee, v204
	v_fmamk_f32 v83, v83, 0x3e0293ee, v204
	v_fmamk_f32 v84, v84, 0x3e0293ee, v204
	v_fmamk_f32 v85, v85, 0x3e0293ee, v204
	v_fmamk_f32 v86, v86, 0x3e0293ee, v204
	v_fmamk_f32 v87, v87, 0x3e0293ee, v204
	v_fmamk_f32 v88, v88, 0x3e0293ee, v204
	v_fmamk_f32 v89, v89, 0x3e0293ee, v204
	v_fmamk_f32 v90, v90, 0x3e0293ee, v204
	v_fmamk_f32 v91, v91, 0x3e0293ee, v204
	v_fmamk_f32 v92, v92, 0x3e0293ee, v204
	v_fmamk_f32 v93, v93, 0x3e0293ee, v204
	v_fmamk_f32 v94, v94, 0x3e0293ee, v204
	v_fmamk_f32 v95, v95, 0x3e0293ee, v204
	v_exp_f32_e32 v160, v80
	v_exp_f32_e32 v175, v81
	v_exp_f32_e32 v161, v82
	v_exp_f32_e32 v174, v83
	v_exp_f32_e32 v162, v84
	v_exp_f32_e32 v173, v85
	v_exp_f32_e32 v163, v86
	v_exp_f32_e32 v172, v87
	v_exp_f32_e32 v164, v88
	v_exp_f32_e32 v171, v89
	v_exp_f32_e32 v165, v90
	v_exp_f32_e32 v170, v91
	v_exp_f32_e32 v166, v92
	v_exp_f32_e32 v169, v93
	v_exp_f32_e32 v167, v94
	v_exp_f32_e32 v168, v95
	v_fmamk_f32 v213, v64, 0x3e0293ee, v204
	v_fmamk_f32 v214, v65, 0x3e0293ee, v204
	v_fmamk_f32 v215, v66, 0x3e0293ee, v204
	v_fmamk_f32 v216, v67, 0x3e0293ee, v204
	v_fmamk_f32 v217, v68, 0x3e0293ee, v204
	v_fmamk_f32 v206, v69, 0x3e0293ee, v204
	v_fmamk_f32 v207, v70, 0x3e0293ee, v204
	v_fmamk_f32 v208, v71, 0x3e0293ee, v204
	v_fmamk_f32 v209, v72, 0x3e0293ee, v204
	v_fmamk_f32 v210, v73, 0x3e0293ee, v204
	v_fmamk_f32 v211, v74, 0x3e0293ee, v204
	v_fmamk_f32 v212, v75, 0x3e0293ee, v204
	v_fmamk_f32 v205, v76, 0x3e0293ee, v204
	v_fmamk_f32 v218, v77, 0x3e0293ee, v204
	v_fmamk_f32 v219, v78, 0x3e0293ee, v204
	v_fmac_f32_e32 v204, 0x3e0293ee, v79
	s_waitcnt lgkmcnt(0)
	s_barrier
	ds_read_b128 v[64:67], v191 offset:32768
	ds_read_b128 v[68:71], v191 offset:40960
	ds_read_b128 v[220:223], v192 offset:32768
	ds_read_b128 v[224:227], v192 offset:40960
	v_exp_f32_e32 v213, v213
	v_exp_f32_e32 v214, v214
	s_waitcnt lgkmcnt(3)
	v_mfma_f32_32x32x16_bf16 v[80:95], v[64:67], v[104:107], 0
	v_exp_f32_e32 v215, v215
	v_exp_f32_e32 v216, v216
	v_exp_f32_e32 v217, v217
	v_exp_f32_e32 v206, v206
	v_exp_f32_e32 v207, v207
	v_exp_f32_e32 v208, v208
	v_exp_f32_e32 v209, v209
	s_waitcnt lgkmcnt(2)
	v_mfma_f32_32x32x16_bf16 v[64:79], v[68:71], v[104:107], 0
	v_exp_f32_e32 v210, v210
	v_exp_f32_e32 v211, v211
	v_exp_f32_e32 v212, v212
	v_exp_f32_e32 v218, v218
	v_exp_f32_e32 v219, v219
	s_waitcnt lgkmcnt(1)
	v_mfma_f32_32x32x16_bf16 v[80:95], v[220:223], v[96:99], v[80:95]
	s_waitcnt lgkmcnt(0)
	v_mfma_f32_32x32x16_bf16 v[64:79], v[224:227], v[96:99], v[64:79]
	ds_read_b128 v[220:223], v193 offset:32768
	ds_read_b128 v[224:227], v193 offset:40960
	s_waitcnt lgkmcnt(1)
	v_mfma_f32_32x32x16_bf16 v[80:95], v[220:223], v[100:103], v[80:95]
	s_waitcnt lgkmcnt(0)
	v_mfma_f32_32x32x16_bf16 v[64:79], v[224:227], v[100:103], v[64:79]
	ds_read_b128 v[220:223], v194 offset:32768
	ds_read_b128 v[224:227], v194 offset:40960
	s_waitcnt lgkmcnt(1)
	v_mfma_f32_32x32x16_bf16 v[80:95], v[220:223], v[108:111], v[80:95]
	s_waitcnt lgkmcnt(0)
	v_mfma_f32_32x32x16_bf16 v[64:79], v[224:227], v[108:111], v[64:79]
	ds_read_b128 v[220:223], v195 offset:32768
	ds_read_b128 v[224:227], v195 offset:40960
	s_waitcnt lgkmcnt(1)
	v_mfma_f32_32x32x16_bf16 v[80:95], v[220:223], v[120:123], v[80:95]
	s_waitcnt lgkmcnt(0)
	v_mfma_f32_32x32x16_bf16 v[64:79], v[224:227], v[120:123], v[64:79]
	ds_read_b128 v[220:223], v196 offset:32768
	ds_read_b128 v[224:227], v196 offset:40960
	s_waitcnt lgkmcnt(1)
	v_mfma_f32_32x32x16_bf16 v[80:95], v[220:223], v[124:127], v[80:95]
	s_waitcnt lgkmcnt(0)
	v_mfma_f32_32x32x16_bf16 v[64:79], v[224:227], v[124:127], v[64:79]
	ds_read_b128 v[220:223], v197 offset:32768
	ds_read_b128 v[224:227], v197 offset:40960
	s_waitcnt lgkmcnt(1)
	v_mfma_f32_32x32x16_bf16 v[80:95], v[220:223], v[112:115], v[80:95]
	s_waitcnt lgkmcnt(0)
	v_mfma_f32_32x32x16_bf16 v[64:79], v[224:227], v[112:115], v[64:79]
	ds_read_b128 v[220:223], v198 offset:32768
	ds_read_b128 v[224:227], v198 offset:40960
	s_waitcnt lgkmcnt(1)
	v_mfma_f32_32x32x16_bf16 v[80:95], v[220:223], v[116:119], v[80:95]
	v_exp_f32_e32 v221, v204
	v_add_f32_e32 v204, 0, v160
	v_add_f32_e32 v204, v175, v204
	v_add_f32_e32 v204, v161, v204
	v_add_f32_e32 v204, v174, v204
	v_add_f32_e32 v204, v162, v204
	v_add_f32_e32 v204, v173, v204
	v_add_f32_e32 v204, v163, v204
	v_add_f32_e32 v204, v172, v204
	v_add_f32_e32 v204, v164, v204
	v_add_f32_e32 v204, v171, v204
	v_add_f32_e32 v204, v165, v204
	v_add_f32_e32 v204, v170, v204
	v_add_f32_e32 v204, v166, v204
	v_add_f32_e32 v204, v169, v204
	v_add_f32_e32 v204, v167, v204
	v_add_f32_e32 v204, v168, v204
	v_add_f32_e32 v204, v213, v204
	v_add_f32_e32 v204, v214, v204
	v_add_f32_e32 v204, v215, v204
	v_add_f32_e32 v204, v216, v204
	v_add_f32_e32 v204, v217, v204
	v_add_f32_e32 v204, v206, v204
	v_add_f32_e32 v204, v207, v204
	v_add_f32_e32 v204, v208, v204
	v_exp_f32_e32 v220, v205
	v_add_f32_e32 v204, v209, v204
	v_add_f32_e32 v204, v210, v204
	s_waitcnt lgkmcnt(0)
	v_mfma_f32_32x32x16_bf16 v[64:79], v[224:227], v[116:119], v[64:79]
	v_add_f32_e32 v204, v211, v204
	v_add_f32_e32 v204, v212, v204
	v_add_f32_e32 v204, v220, v204
	v_add_f32_e32 v204, v218, v204
	v_add_f32_e32 v204, v219, v204
	v_add_f32_e32 v204, v221, v204
	v_mov_b32_e32 v205, v204
	v_cvt_pk_bf16_f32 v160, v160, v175
	v_cvt_pk_bf16_f32 v161, v161, v174
	v_cvt_pk_bf16_f32 v162, v162, v173
	v_cvt_pk_bf16_f32 v163, v163, v172
	v_cvt_pk_bf16_f32 v164, v164, v171
	v_cvt_pk_bf16_f32 v165, v165, v170
	v_cvt_pk_bf16_f32 v166, v166, v169
	v_cvt_pk_bf16_f32 v167, v167, v168
	v_cvt_pk_bf16_f32 v168, v213, v214
	v_cvt_pk_bf16_f32 v169, v215, v216
	v_cvt_pk_bf16_f32 v170, v217, v206
	v_cvt_pk_bf16_f32 v171, v207, v208
	v_cvt_pk_bf16_f32 v172, v209, v210
	v_cvt_pk_bf16_f32 v173, v211, v212
	v_cvt_pk_bf16_f32 v174, v220, v218
	v_cvt_pk_bf16_f32 v175, v219, v221
	s_nop 1
	v_permlane32_swap_b32_e32 v204, v205
	v_permlane32_swap_b32_e32 v160, v162
	v_permlane32_swap_b32_e32 v161, v163
	v_permlane32_swap_b32_e32 v164, v166
	v_permlane32_swap_b32_e32 v165, v167
	v_permlane32_swap_b32_e32 v168, v170
	v_permlane32_swap_b32_e32 v169, v171
	v_permlane32_swap_b32_e32 v172, v174
	v_permlane32_swap_b32_e32 v173, v175
	ds_read_b64_tr_b16 v[206:207], v185 offset:0
	ds_read_b64_tr_b16 v[208:209], v185 offset:0x800
	ds_read_b64_tr_b16 v[210:211], v185 offset:0x1000
	ds_read_b64_tr_b16 v[212:213], v185 offset:0x1800
	ds_read_b64_tr_b16 v[214:215], v185 offset:0x2000
	ds_read_b64_tr_b16 v[216:217], v185 offset:0x2800
	ds_read_b64_tr_b16 v[218:219], v185 offset:0x3000
	ds_read_b64_tr_b16 v[220:221], v185 offset:0x3800
	s_cmp_gt_u32 s80, 32
	s_cselect_b64 s[14:15], -1, 0
	s_and_b64 vcc, exec, s[14:15]
	s_cbranch_vccnz .LBB0_466
; #define SBAR() __builtin_amdgcn_sched_barrier(0)
; #define SLOAD(i, k0) do { sr_[i].vs0 = St::ld8(&Vh[(long)((k0) + sr) * LDK + sc]); sr_[i].vs1 = St::ld8(&Vh[(long)((k0) + 32 + sr) * LDK + sc]); \
;     sr_[i].ks0 = St::ld8(&Kh[(long)((k0) + sr) * LDK + sc]); sr_[i].ks1 = St::ld8(&Kh[(long)((k0) + 32 + sr) * LDK + sc]); } while (0)
; #define SWAIT() do { asm volatile("s_waitcnt vmcnt(4)" ::: "memory"); } while (0)
; #define RESC(a) do { if (__any((a) < 1.f)) { if (hi == 0) al_l[r32] = (a); asm volatile("s_waitcnt lgkmcnt(0)" ::: "memory"); \
;     for (int d = 0; d < 4; ++d) for (int r = 0; r < 16; ++r) o[d][r] *= al_l[crow(r, hi)]; } } while (0)
; template <int D0> __device__ __forceinline__ void pv_one(f32x16& od, int vb, bf16x8 pa0, bf16x8 pa1, bf16x8 pa2, bf16x8 pa3) {
;   const s16x4 l0 = tr_read<v_rd_off(D0, 0, 0)>(vb), h0 = tr_read<v_rd_off(D0, 0, 1)>(vb), l1 = tr_read<v_rd_off(D0, 1, 0)>(vb), h1 = tr_read<v_rd_off(D0, 1, 1)>(vb);
;   const s16x4 l2 = tr_read<v_rd_off(D0, 2, 0)>(vb), h2 = tr_read<v_rd_off(D0, 2, 1)>(vb), l3 = tr_read<v_rd_off(D0, 3, 0)>(vb), h3 = tr_read<v_rd_off(D0, 3, 1)>(vb);
;   asm volatile("s_waitcnt lgkmcnt(0)" ::: "memory"); SBAR();
;     ...
;   od = __builtin_amdgcn_mfma_f32_32x32x16_bf16(pa0, PK(l0, h0), od, 0, 0, 0);
;   od = __builtin_amdgcn_mfma_f32_32x32x16_bf16(pa1, PK(l1, h1), od, 0, 0, 0);
;   od = __builtin_amdgcn_mfma_f32_32x32x16_bf16(pa2, PK(l2, h2), od, 0, 0, 0);
;   od = __builtin_amdgcn_mfma_f32_32x32x16_bf16(pa3, PK(l3, h3), od, 0, 0, 0);
;     ...
; }
; __device__ __forceinline__ void pv_d0(f32x16* o, int vb, bf16x8 pa0, bf16x8 pa1, bf16x8 pa2, bf16x8 pa3) {
;   pv_one<0>(o[0], vb, pa0, pa1, pa2, pa3); pv_one<1>(o[1], vb, pa0, pa1, pa2, pa3); pv_one<2>(o[2], vb, pa0, pa1, pa2, pa3); pv_one<3>(o[3], vb, pa0, pa1, pa2, pa3);
; __device__ __forceinline__ void attn_unit(const bf16* Qb, const bf16* __restrict__ Kh, const bf16* __restrict__ Vh, bf16* Ob, int seq, char* lds,
;                                           const float* __restrict__ rope, const float* __restrict__ qg, const int mk_wid) {
;     ...
;     if (j + 3 < NT) SLOAD(SE, (j + 3) * KVBLK); SBAR();
;     pv_d0(o, vb0 + (int)SHM_V, pa0, pa1, pa2, pa3); partialSM(pA0, pA1, m_reg, mnA, alA);
;     __syncthreads(); SWAIT(); SWRITE(1, SO);
;     RESC(alA); __syncthreads();
	v_add_co_u32_e32 v128, vcc, 0xffffc000, v178
	s_nop 1
	v_addc_co_u32_e32 v129, vcc, -1, v179, vcc
	v_add_co_u32_e32 v132, vcc, 0xfedfc000, v178
	s_nop 1
	v_addc_co_u32_e32 v133, vcc, -1, v179, vcc
	v_add_co_u32_e32 v140, vcc, 0xfee00000, v178
	global_load_dwordx4 v[128:131], v[128:129], off
	s_nop 0
	global_load_dwordx4 v[132:135], v[132:133], off
	v_addc_co_u32_e32 v141, vcc, -1, v179, vcc
	global_load_dwordx4 v[136:139], v[178:179], off
	s_nop 0
	global_load_dwordx4 v[140:143], v[140:141], off
.LBB0_466:
	s_waitcnt lgkmcnt(0)
	s_nop 0
	v_mfma_f32_32x32x16_bf16 v[0:15], v[160:163], v[206:209], v[0:15]
	ds_read_b64_tr_b16 v[206:207], v185 offset:0x200
	ds_read_b64_tr_b16 v[208:209], v185 offset:0xa00
	v_mfma_f32_32x32x16_bf16 v[0:15], v[164:167], v[210:213], v[0:15]
	ds_read_b64_tr_b16 v[210:211], v185 offset:0x1200
	ds_read_b64_tr_b16 v[212:213], v185 offset:0x1a00
	v_mfma_f32_32x32x16_bf16 v[0:15], v[168:171], v[214:217], v[0:15]
	ds_read_b64_tr_b16 v[214:215], v185 offset:0x2200
	ds_read_b64_tr_b16 v[216:217], v185 offset:0x2a00
	ds_read_b64_tr_b16 v[222:223], v185 offset:0x3200
	ds_read_b64_tr_b16 v[224:225], v185 offset:0x3a00
	s_waitcnt lgkmcnt(0)
	v_mfma_f32_32x32x16_bf16 v[0:15], v[172:175], v[218:221], v[0:15]
	v_mfma_f32_32x32x16_bf16 v[48:63], v[160:163], v[206:209], v[48:63]
	ds_read_b64_tr_b16 v[206:207], v185 offset:0x400
	ds_read_b64_tr_b16 v[208:209], v185 offset:0xc00
	v_mfma_f32_32x32x16_bf16 v[48:63], v[164:167], v[210:213], v[48:63]
	ds_read_b64_tr_b16 v[210:211], v185 offset:0x1400
	ds_read_b64_tr_b16 v[212:213], v185 offset:0x1c00
	v_mfma_f32_32x32x16_bf16 v[48:63], v[168:171], v[214:217], v[48:63]
	ds_read_b64_tr_b16 v[214:215], v185 offset:0x2400
	ds_read_b64_tr_b16 v[216:217], v185 offset:0x2c00
	ds_read_b64_tr_b16 v[218:219], v185 offset:0x3400
	ds_read_b64_tr_b16 v[220:221], v185 offset:0x3c00
	s_waitcnt lgkmcnt(0)
	v_mfma_f32_32x32x16_bf16 v[48:63], v[172:175], v[222:225], v[48:63]
	v_mfma_f32_32x32x16_bf16 v[32:47], v[160:163], v[206:209], v[32:47]
	ds_read_b64_tr_b16 v[206:207], v185 offset:0x600
	ds_read_b64_tr_b16 v[208:209], v185 offset:0xe00
	v_mfma_f32_32x32x16_bf16 v[32:47], v[164:167], v[210:213], v[32:47]
	ds_read_b64_tr_b16 v[210:211], v185 offset:0x1600
	ds_read_b64_tr_b16 v[212:213], v185 offset:0x1e00
	v_mfma_f32_32x32x16_bf16 v[32:47], v[168:171], v[214:217], v[32:47]
	ds_read_b64_tr_b16 v[214:215], v185 offset:0x2600
	ds_read_b64_tr_b16 v[216:217], v185 offset:0x2e00
	ds_read_b64_tr_b16 v[222:223], v185 offset:0x3600
	ds_read_b64_tr_b16 v[224:225], v185 offset:0x3e00
	s_waitcnt lgkmcnt(0)
	v_mfma_f32_32x32x16_bf16 v[32:47], v[172:175], v[218:221], v[32:47]
	v_mfma_f32_32x32x16_bf16 v[16:31], v[160:163], v[206:209], v[16:31]
	v_max_f32_e32 v218, v81, v81
	v_max_f32_e32 v219, v80, v80
	v_max_f32_e32 v218, v219, v218
	v_max3_f32 v218, v218, v82, v83
	v_max3_f32 v218, v218, v84, v85
	v_max3_f32 v160, v218, v86, v87
	v_max3_f32 v160, v160, v88, v89
	v_max3_f32 v160, v160, v90, v91
	v_mfma_f32_32x32x16_bf16 v[16:31], v[164:167], v[210:213], v[16:31]
	v_max3_f32 v160, v160, v92, v93
	v_max3_f32 v160, v160, v94, v95
	v_max3_f32 v160, v160, v64, v65
	v_max3_f32 v160, v160, v66, v67
	v_max3_f32 v160, v160, v68, v69
	v_max3_f32 v160, v160, v70, v71
	v_max3_f32 v160, v160, v72, v73
	v_max3_f32 v160, v160, v74, v75
	v_mfma_f32_32x32x16_bf16 v[16:31], v[168:171], v[214:217], v[16:31]
	v_max3_f32 v160, v160, v76, v77
	v_max3_f32 v160, v160, v78, v79
	v_mov_b32_e32 v161, v160
	s_nop 1
	v_permlane32_swap_b32_e32 v160, v161
	v_max_f32_e32 v161, v161, v161
	v_max_f32_e32 v160, v160, v160
	v_max_f32_e32 v160, v160, v161
	v_max_f32_e32 v162, v203, v203
	v_sub_f32_e32 v161, v160, v203
	v_max_f32_e32 v160, v162, v160
	v_mfma_f32_32x32x16_bf16 v[16:31], v[172:175], v[222:225], v[16:31]
	v_sub_f32_e32 v162, v203, v160
	v_mul_f32_e32 v162, 0x3e0293ee, v162
	v_exp_f32_e32 v162, v162
	v_cmp_ge_f32_e32 vcc, s74, v161
	s_cmp_eq_u64 vcc, exec
	s_cselect_b64 s[4:5], -1, 0
	s_barrier
	s_waitcnt vmcnt(4)
	v_cndmask_b32_e64 v161, v162, 1.0, s[4:5]
	v_cmp_gt_f32_e32 vcc, 1.0, v161
	s_waitcnt vmcnt(3)
	ds_write_b128 v187, v[144:147] offset:16384
	s_waitcnt vmcnt(2)
	ds_write_b128 v188, v[148:151] offset:16384
	s_waitcnt vmcnt(1)
	ds_write_b128 v189, v[152:155] offset:49152
	s_waitcnt vmcnt(0)
	ds_write_b128 v190, v[156:159] offset:49152
	s_cbranch_vccz .LBB0_470
	s_and_saveexec_b64 s[16:17], s[2:3]
	ds_write_b32 v183, v161 offset:128
	s_or_b64 exec, exec, s[16:17]
	s_waitcnt lgkmcnt(0)
	v_add_u32_e32 v156, s67, v176
	ds_read_b128 v[144:147], v156 offset:224
	ds_read_b128 v[148:151], v156 offset:192
	ds_read_b128 v[152:155], v156 offset:160
	ds_read_b128 v[156:159], v156 offset:128
	s_waitcnt lgkmcnt(3)
	v_pk_mul_f32 v[12:13], v[12:13], v[144:145]
	s_waitcnt lgkmcnt(2)
	v_pk_mul_f32 v[8:9], v[8:9], v[148:149]
	s_waitcnt lgkmcnt(1)
	v_pk_mul_f32 v[4:5], v[4:5], v[152:153]
	v_pk_mul_f32 v[14:15], v[14:15], v[146:147]
	v_pk_mul_f32 v[10:11], v[10:11], v[150:151]
	v_pk_mul_f32 v[6:7], v[6:7], v[154:155]
	s_waitcnt lgkmcnt(0)
	v_pk_mul_f32 v[2:3], v[2:3], v[158:159]
	v_pk_mul_f32 v[0:1], v[0:1], v[156:157]
	v_pk_mul_f32 v[60:61], v[60:61], v[144:145]
	v_pk_mul_f32 v[56:57], v[56:57], v[148:149]
	v_pk_mul_f32 v[52:53], v[52:53], v[152:153]
	v_pk_mul_f32 v[62:63], v[62:63], v[146:147]
	v_pk_mul_f32 v[58:59], v[58:59], v[150:151]
	v_pk_mul_f32 v[54:55], v[54:55], v[154:155]
	v_pk_mul_f32 v[50:51], v[50:51], v[158:159]
	v_pk_mul_f32 v[48:49], v[48:49], v[156:157]
	v_pk_mul_f32 v[44:45], v[44:45], v[144:145]
	v_pk_mul_f32 v[40:41], v[40:41], v[148:149]
	v_pk_mul_f32 v[36:37], v[36:37], v[152:153]
	v_pk_mul_f32 v[46:47], v[46:47], v[146:147]
	v_pk_mul_f32 v[42:43], v[42:43], v[150:151]
	v_pk_mul_f32 v[38:39], v[38:39], v[154:155]
	v_pk_mul_f32 v[34:35], v[34:35], v[158:159]
	v_pk_mul_f32 v[32:33], v[32:33], v[156:157]
	v_pk_mul_f32 v[28:29], v[28:29], v[144:145]
	v_pk_mul_f32 v[24:25], v[24:25], v[148:149]
	v_pk_mul_f32 v[20:21], v[20:21], v[152:153]
	v_pk_mul_f32 v[30:31], v[30:31], v[146:147]
	v_pk_mul_f32 v[26:27], v[26:27], v[150:151]
	v_pk_mul_f32 v[22:23], v[22:23], v[154:155]
	v_pk_mul_f32 v[18:19], v[18:19], v[158:159]
	v_pk_mul_f32 v[16:17], v[16:17], v[156:157]
